# attention: static s_setprio 1 for waves 0-3 (older half)
# baseline (speedup 1.0000x reference)
.LBB0_152:
	v_readlane_b32 s2, v252, 10
	v_mbcnt_lo_u32_b32 v237, -1, 0
	v_mbcnt_hi_u32_b32 v237, -1, v237
	s_nop 1
	v_add_u32_e32 v34, s2, v237
	s_movk_i32 s2, 0x80
	v_readfirstlane_b32 s6, v34
	v_cmp_gt_i32_e32 vcc, s2, v34
	s_cmpk_gt_u32 s6, 0xff
	s_cbranch_scc1 .Latt_prio_done
	s_setprio 1
